# phase-4 V^T epilogue regenerated: row-scale vectors computed up front, one address per column, 16-byte stores via v_permlane16_swap
# speedup vs baseline: 1.0668x; 1.0059x over previous
; #define GLDS16(gp, lp) __builtin_amdgcn_global_load_lds((const unsigned*)(gp), (__attribute__((address_space(3))) unsigned*)(lp), 16, 0, 0)
; template <bool SWAP, class Epi, bool THIN = false> ...
;     ...
;     unsigned ap[4], bp[4];
; #pragma unroll
;     for (int i = 0; i < 4; ++i) {
;       const int r = (tid >> 3) + 64 * i;
;       const int cs = tid & 7;
;       const int c = ((cs ^ ((r >> 1) & 7)) << 3);
;       const int sub = 2 * mt + (r >> 7);
;       const int g = sub / tpg, ti = sub - g * tpg;
;       int rig = ti * step - halo + (r & 127); rig = rig < 0 ? 0 : (rig > grows - 1 ? grows - 1 : rig);
;       ap[i] = (unsigned)((g * a_gstride + a_goff + rig) * lda + c);
;       int br = nt * 256 + r; br = br > N - 1 ? N - 1 : br;
;       bp[i] = (unsigned)(br * K + c);
;     }
;     const bool have_next = false;
;     f32x4 acc[4][8];
; #pragma unroll
;     for (int m = 0; m < 4; ++m)
; #pragma unroll
;       for (int n = 0; n < 8; ++n) acc[m][n] = (f32x4){0.f, 0.f, 0.f, 0.f};
;     if (!pre_issued) {
; #pragma unroll
;       for (int i = 0; i < 4; ++i) { GLDS16(A + (size_t)ap[i], smem + tid * 16 + i * 8192); GLDS16(Bt + (size_t)bp[i], smem + 32768 + tid * 16 + i * 8192); }
;     }
;     pre_issued = have_next;
;     for (int st = 0; st < ns; ++st) {
;       asm volatile("s_waitcnt vmcnt(0)" ::: "memory");
;       __builtin_amdgcn_s_barrier();
;       asm volatile("" ::: "memory");
;       if (st + 1 < ns) {
;         char* nb = smem + ((st + 1) & 1) * 65536;
;         const int ko = (st + 1) * 64;
; #pragma unroll
;         for (int i = 0; i < 4; ++i) { GLDS16(A + (size_t)(ap[i] + ko), nb + tid * 16 + i * 8192); GLDS16(Bt + (size_t)(bp[i] + ko), nb + 32768 + tid * 16 + i * 8192); }
;       }
;       const char* sa = smem + (st & 1) * 65536 + (wr * 64 + fr) * 128;
;       const char* sb = smem + (st & 1) * 65536 + 32768 + (wc * 128 + fr) * 128;
;     ...
;       for (int m = 0; m < 4; ++m) afA[m] = *(const bf16x8*)(sa + m * 2048 + ((fq ^ swz) << 4));
; #pragma unroll
;       for (int n = 0; n < 2; ++n) bfb[0][n] = *(const bf16x8*)(sb + n * 2048 + ((fq ^ swz) << 4));
.LBB0_1887:
	s_add_i32 s4, s3, 0xfffffd60
	s_ashr_i32 s5, s4, 31
	s_lshr_b32 s5, s5, 27
	s_add_i32 s4, s4, s5
	s_ashr_i32 s4, s4, 5
	s_lshl_b32 s5, s4, 4
	s_and_b32 s6, s33, 14
	s_or_b32 s5, s5, s6
	v_add_u32_e32 v2, s5, v149
	v_mul_hi_i32 v3, v2, s51
	v_lshrrev_b32_e32 v4, 31, v3
	v_ashrrev_i32_e32 v3, 2, v3
	v_add_u32_e32 v4, v3, v4
	v_mad_u64_u32 v[2:3], s[6:7], v4, s56, v[2:3]
	v_lshl_or_b32 v3, v2, 7, v150
	v_min_i32_e32 v3, 0x8ff, v3
	v_cmp_lt_i32_e32 vcc, -1, v2
	s_lshl_b32 s4, s4, 10
	s_sub_i32 s4, s49, s4
	v_cndmask_b32_e32 v2, 0, v3, vcc
	v_mad_u64_u32 v[2:3], s[6:7], v4, s57, v[2:3]
	s_and_b32 s4, s4, 0xffffff00
	v_mad_u64_u32 v[2:3], s[6:7], v2, s58, v[130:131]
	v_add_u32_e32 v3, s4, v131
	v_min_i32_e32 v3, 0x3ff, v3
	v_add_u32_e32 v4, s5, v152
	v_lshl_or_b32 v132, v3, 8, v130
	v_mul_hi_i32 v3, v4, s51
	v_lshrrev_b32_e32 v5, 31, v3
	v_ashrrev_i32_e32 v3, 2, v3
	v_add_u32_e32 v3, v3, v5
	v_mad_u64_u32 v[4:5], s[6:7], v3, s56, v[4:5]
	v_lshl_or_b32 v5, v4, 7, v153
	v_min_i32_e32 v5, 0x8ff, v5
	v_cmp_lt_i32_e32 vcc, -1, v4
	v_add_u32_e32 v6, s5, v155
	v_add_u32_e32 v8, s5, v157
	v_cndmask_b32_e32 v4, 0, v5, vcc
	v_mad_u64_u32 v[4:5], s[6:7], v3, s57, v[4:5]
	v_add_u32_e32 v3, s4, v151
	v_min_i32_e32 v3, 0x3ff, v3
	v_mad_u64_u32 v[4:5], s[6:7], v4, s58, v[130:131]
	v_lshl_or_b32 v12, v3, 8, v130
	v_mul_hi_i32 v3, v6, s51
	v_lshrrev_b32_e32 v5, 31, v3
	v_ashrrev_i32_e32 v3, 2, v3
	v_add_u32_e32 v3, v3, v5
	v_mad_u64_u32 v[6:7], s[6:7], v3, s56, v[6:7]
	v_lshl_or_b32 v5, v6, 7, v150
	v_min_i32_e32 v5, 0x8ff, v5
	v_cmp_lt_i32_e32 vcc, -1, v6
	v_readfirstlane_b32 s21, v148
	s_mov_b32 m0, s21
	v_cndmask_b32_e32 v6, 0, v5, vcc
	v_mad_u64_u32 v[6:7], s[6:7], v3, s57, v[6:7]
	v_add_u32_e32 v3, s4, v154
	v_min_i32_e32 v3, 0x3ff, v3
	v_lshl_or_b32 v14, v3, 8, v130
	v_mul_hi_i32 v3, v8, s51
	v_lshrrev_b32_e32 v5, 31, v3
	v_ashrrev_i32_e32 v3, 2, v3
	v_add_u32_e32 v3, v3, v5
	v_mad_u64_u32 v[8:9], s[6:7], v3, s56, v[8:9]
	v_lshl_or_b32 v5, v8, 7, v158
	v_min_i32_e32 v5, 0x8ff, v5
	v_cmp_lt_i32_e32 vcc, -1, v8
	v_readfirstlane_b32 s15, v159
	v_readfirstlane_b32 s14, v160
	v_cndmask_b32_e32 v8, 0, v5, vcc
	v_mad_u64_u32 v[8:9], s[6:7], v3, s57, v[8:9]
	v_add_u32_e32 v3, s4, v156
	v_min_i32_e32 v3, 0x3ff, v3
	v_lshl_or_b32 v16, v3, 8, v130
	v_mov_b32_e32 v3, v133
	v_lshl_add_u64 v[10:11], v[2:3], 1, s[28:29]
	global_load_lds_dwordx4 v[10:11], off
	v_lshl_add_u64 v[10:11], v[132:133], 1, s[34:35]
	s_mov_b32 m0, s15
	v_mov_b32_e32 v5, v133
	v_mad_u64_u32 v[6:7], s[6:7], v6, s58, v[130:131]
	global_load_lds_dwordx4 v[10:11], off
	v_lshl_add_u64 v[18:19], v[4:5], 1, s[28:29]
	s_mov_b32 m0, s14
	v_mov_b32_e32 v13, v133
	v_readfirstlane_b32 s17, v161
	global_load_lds_dwordx4 v[18:19], off
	v_lshl_add_u64 v[12:13], v[12:13], 1, s[34:35]
	s_mov_b32 m0, s17
	v_mov_b32_e32 v7, v133
	v_readfirstlane_b32 s16, v162
	v_mad_u64_u32 v[8:9], s[6:7], v8, s58, v[130:131]
	global_load_lds_dwordx4 v[12:13], off
	v_lshl_add_u64 v[18:19], v[6:7], 1, s[28:29]
	s_mov_b32 m0, s16
	v_mov_b32_e32 v15, v133
	v_readfirstlane_b32 s19, v163
	global_load_lds_dwordx4 v[18:19], off
	v_lshl_add_u64 v[14:15], v[14:15], 1, s[34:35]
	s_mov_b32 m0, s19
	v_mov_b32_e32 v9, v133
	v_readfirstlane_b32 s18, v164
	global_load_lds_dwordx4 v[14:15], off
	v_lshl_add_u64 v[18:19], v[8:9], 1, s[28:29]
	s_mov_b32 m0, s18
	v_mov_b32_e32 v17, v133
	v_readfirstlane_b32 s20, v165
	global_load_lds_dwordx4 v[18:19], off
	v_lshl_add_u64 v[16:17], v[16:17], 1, s[34:35]
	s_mov_b32 m0, s20
	v_add_u32_e32 v132, 64, v2
	global_load_lds_dwordx4 v[16:17], off
	v_readfirstlane_b32 s13, v166
	s_waitcnt vmcnt(0)
	s_barrier
	v_lshl_add_u64 v[18:19], v[132:133], 1, s[28:29]
	s_mov_b32 m0, s13
	v_readfirstlane_b32 s8, v167
	global_load_lds_dwordx4 v[18:19], off
	v_lshl_add_u64 v[18:19], v[10:11], 0, s[38:39]
	s_mov_b32 m0, s8
	v_add_u32_e32 v132, 64, v4
	v_readfirstlane_b32 s7, v168
	global_load_lds_dwordx4 v[18:19], off
	v_lshl_add_u64 v[18:19], v[132:133], 1, s[28:29]
	s_mov_b32 m0, s7
	v_readfirstlane_b32 s6, v169
	global_load_lds_dwordx4 v[18:19], off
	v_lshl_add_u64 v[18:19], v[12:13], 0, s[38:39]
	s_mov_b32 m0, s6
	v_add_u32_e32 v132, 64, v6
	v_readfirstlane_b32 s9, v170
	global_load_lds_dwordx4 v[18:19], off
	v_lshl_add_u64 v[18:19], v[132:133], 1, s[28:29]
	s_mov_b32 m0, s9
	v_readfirstlane_b32 s10, v171
	global_load_lds_dwordx4 v[18:19], off
	v_lshl_add_u64 v[18:19], v[14:15], 0, s[38:39]
	s_mov_b32 m0, s10
	v_add_u32_e32 v132, 64, v8
	v_readfirstlane_b32 s11, v172
	global_load_lds_dwordx4 v[18:19], off
	v_lshl_add_u64 v[18:19], v[132:133], 1, s[28:29]
	s_mov_b32 m0, s11
	v_readfirstlane_b32 s12, v173
	global_load_lds_dwordx4 v[18:19], off
	v_lshl_add_u64 v[18:19], v[16:17], 0, s[38:39]
	s_mov_b32 m0, s12
	s_nop 0
	global_load_lds_dwordx4 v[18:19], off
	ds_read_b128 v[18:21], v174
	ds_read_b128 v[22:25], v174 offset:2048
	ds_read_b128 v[26:29], v174 offset:4096
	ds_read_b128 v[30:33], v174 offset:6144
	ds_read_b128 v[34:37], v175 offset:32768
	ds_read_b128 v[38:41], v175 offset:34816
	ds_read_b128 v[42:45], v175 offset:36864
	ds_read_b128 v[46:49], v175 offset:38912
	ds_read_b128 v[74:77], v175 offset:40960
	ds_read_b128 v[78:81], v175 offset:43008
	s_waitcnt lgkmcnt(0)
; template <bool SWAP, class Epi, bool THIN = false> ...
;     ...
;       bf16x8 afA[4], afB[4], bfb[2][2];
; #pragma unroll
;       for (int m = 0; m < 4; ++m) afA[m] = *(const bf16x8*)(sa + m * 2048 + ((fq ^ swz) << 4));
; #pragma unroll
;       for (int n = 0; n < 2; ++n) bfb[0][n] = *(const bf16x8*)(sb + n * 2048 + ((fq ^ swz) << 4));
; #pragma unroll
;       for (int gq = 0; gq < 8; ++gq) {
;         const int ks = gq >> 2, nh = gq & 3;
;         if (gq < 7) {
;           const int ks2 = (gq + 1) >> 2, nh2 = (gq + 1) & 3;
; #pragma unroll
;           for (int n = 0; n < 2; ++n) bfb[(gq + 1) & 1][n] = *(const bf16x8*)(sb + (nh2 * 2 + n) * 2048 + (((ks2 * 4 + fq) ^ swz) << 4));
;         }
;         if (gq == 3) {
; #pragma unroll
;           for (int m = 0; m < 4; ++m) afB[m] = *(const bf16x8*)(sa + m * 2048 + (((4 + fq) ^ swz) << 4));
;         }
;         __builtin_amdgcn_sched_barrier(0);
; #pragma unroll
;         for (int m = 0; m < 4; ++m)
; #pragma unroll
;           for (int n = 0; n < 2; ++n) {
;             const bf16x8 av = ks ? afB[m] : afA[m];
;             acc[m][nh * 2 + n] = SWAP ? __builtin_amdgcn_mfma_f32_16x16x32_bf16(bfb[gq & 1][n], av, acc[m][nh * 2 + n], 0, 0, 0)
;                                       : __builtin_amdgcn_mfma_f32_16x16x32_bf16(av, bfb[gq & 1][n], acc[m][nh * 2 + n], 0, 0, 0);
;           }
;       }
;       }
;     }
	v_mfma_f32_16x16x32_bf16 v[50:53], v[18:21], v[34:37], 0
	v_mfma_f32_16x16x32_bf16 v[54:57], v[18:21], v[38:41], 0
	v_mfma_f32_16x16x32_bf16 v[58:61], v[22:25], v[34:37], 0
	v_mfma_f32_16x16x32_bf16 v[62:65], v[22:25], v[38:41], 0
	v_mfma_f32_16x16x32_bf16 v[66:69], v[26:29], v[34:37], 0
	v_mfma_f32_16x16x32_bf16 v[70:73], v[26:29], v[38:41], 0
	v_mfma_f32_16x16x32_bf16 v[34:37], v[30:33], v[34:37], 0
	v_mfma_f32_16x16x32_bf16 v[38:41], v[30:33], v[38:41], 0
	ds_read_b128 v[106:109], v175 offset:45056
	ds_read_b128 v[110:113], v175 offset:47104
	v_mfma_f32_16x16x32_bf16 v[82:85], v[18:21], v[42:45], 0
	v_mfma_f32_16x16x32_bf16 v[86:89], v[18:21], v[46:49], 0
	v_mfma_f32_16x16x32_bf16 v[90:93], v[22:25], v[42:45], 0
	v_mfma_f32_16x16x32_bf16 v[94:97], v[22:25], v[46:49], 0
	v_mfma_f32_16x16x32_bf16 v[98:101], v[26:29], v[42:45], 0
	v_mfma_f32_16x16x32_bf16 v[102:105], v[26:29], v[46:49], 0
	v_mfma_f32_16x16x32_bf16 v[42:45], v[30:33], v[42:45], 0
	v_mfma_f32_16x16x32_bf16 v[46:49], v[30:33], v[46:49], 0
	ds_read_b128 v[142:145], v176 offset:32768
	ds_read_b128 v[182:185], v176 offset:34816
	ds_read_b128 v[186:189], v177
	ds_read_b128 v[190:193], v177 offset:2048
	ds_read_b128 v[194:197], v177 offset:4096
	ds_read_b128 v[198:201], v177 offset:6144
	v_mfma_f32_16x16x32_bf16 v[114:117], v[18:21], v[74:77], 0
	v_mfma_f32_16x16x32_bf16 v[118:121], v[18:21], v[78:81], 0
	v_mfma_f32_16x16x32_bf16 v[122:125], v[22:25], v[74:77], 0
	v_mfma_f32_16x16x32_bf16 v[126:129], v[22:25], v[78:81], 0
	v_mfma_f32_16x16x32_bf16 v[134:137], v[26:29], v[74:77], 0
	v_mfma_f32_16x16x32_bf16 v[138:141], v[26:29], v[78:81], 0
	v_mfma_f32_16x16x32_bf16 v[74:77], v[30:33], v[74:77], 0
	v_mfma_f32_16x16x32_bf16 v[78:81], v[30:33], v[78:81], 0
	ds_read_b128 v[214:217], v176 offset:36864
	ds_read_b128 v[218:221], v176 offset:38912
	s_waitcnt lgkmcnt(0)
	v_mfma_f32_16x16x32_bf16 v[202:205], v[18:21], v[106:109], 0
	v_mfma_f32_16x16x32_bf16 v[18:21], v[18:21], v[110:113], 0
	v_mfma_f32_16x16x32_bf16 v[206:209], v[22:25], v[106:109], 0
	v_mfma_f32_16x16x32_bf16 v[22:25], v[22:25], v[110:113], 0
	v_mfma_f32_16x16x32_bf16 v[210:213], v[26:29], v[106:109], 0
	v_mfma_f32_16x16x32_bf16 v[26:29], v[26:29], v[110:113], 0
	v_mfma_f32_16x16x32_bf16 v[106:109], v[30:33], v[106:109], 0
	v_mfma_f32_16x16x32_bf16 v[30:33], v[30:33], v[110:113], 0
	v_mfma_f32_16x16x32_bf16 v[50:53], v[186:189], v[142:145], v[50:53]
	v_mfma_f32_16x16x32_bf16 v[58:61], v[190:193], v[142:145], v[58:61]
	v_mfma_f32_16x16x32_bf16 v[66:69], v[194:197], v[142:145], v[66:69]
	v_mfma_f32_16x16x32_bf16 v[34:37], v[198:201], v[142:145], v[34:37]
	ds_read_b128 v[110:113], v176 offset:40960
	ds_read_b128 v[142:145], v176 offset:43008
	v_mfma_f32_16x16x32_bf16 v[54:57], v[186:189], v[182:185], v[54:57]
	v_mfma_f32_16x16x32_bf16 v[62:65], v[190:193], v[182:185], v[62:65]
	v_mfma_f32_16x16x32_bf16 v[70:73], v[194:197], v[182:185], v[70:73]
	v_mfma_f32_16x16x32_bf16 v[38:41], v[198:201], v[182:185], v[38:41]
	v_mfma_f32_16x16x32_bf16 v[82:85], v[186:189], v[214:217], v[82:85]
	v_mfma_f32_16x16x32_bf16 v[90:93], v[190:193], v[214:217], v[90:93]
	v_mfma_f32_16x16x32_bf16 v[98:101], v[194:197], v[214:217], v[98:101]
	v_mfma_f32_16x16x32_bf16 v[42:45], v[198:201], v[214:217], v[42:45]
	ds_read_b128 v[182:185], v176 offset:45056
	ds_read_b128 v[214:217], v176 offset:47104
	v_mfma_f32_16x16x32_bf16 v[86:89], v[186:189], v[218:221], v[86:89]
	v_mfma_f32_16x16x32_bf16 v[94:97], v[190:193], v[218:221], v[94:97]
	v_mfma_f32_16x16x32_bf16 v[102:105], v[194:197], v[218:221], v[102:105]
	v_mfma_f32_16x16x32_bf16 v[46:49], v[198:201], v[218:221], v[46:49]
	s_waitcnt lgkmcnt(0)
	v_mfma_f32_16x16x32_bf16 v[114:117], v[186:189], v[110:113], v[114:117]
	v_mfma_f32_16x16x32_bf16 v[118:121], v[186:189], v[142:145], v[118:121]
	v_mfma_f32_16x16x32_bf16 v[122:125], v[190:193], v[110:113], v[122:125]
	v_mfma_f32_16x16x32_bf16 v[126:129], v[190:193], v[142:145], v[126:129]
	v_mfma_f32_16x16x32_bf16 v[134:137], v[194:197], v[110:113], v[134:137]
	v_mfma_f32_16x16x32_bf16 v[138:141], v[194:197], v[142:145], v[138:141]
	v_mfma_f32_16x16x32_bf16 v[74:77], v[198:201], v[110:113], v[74:77]
	v_mfma_f32_16x16x32_bf16 v[78:81], v[198:201], v[142:145], v[78:81]
	v_add_u32_e32 v132, 0x80, v2
	s_mov_b32 m0, s21
	s_waitcnt vmcnt(0)
	s_barrier
; template <bool SWAP, class Epi, bool THIN = false> ...
;     ...
;     for (int st = 0; st < ns; ++st) {
;       asm volatile("s_waitcnt vmcnt(0)" ::: "memory");
;       __builtin_amdgcn_s_barrier();
;       asm volatile("" ::: "memory");
;       if (st + 1 < ns) {
;         char* nb = smem + ((st + 1) & 1) * 65536;
;         const int ko = (st + 1) * 64;
; #pragma unroll
;         for (int i = 0; i < 4; ++i) { GLDS16(A + (size_t)(ap[i] + ko), nb + tid * 16 + i * 8192); GLDS16(Bt + (size_t)(bp[i] + ko), nb + 32768 + tid * 16 + i * 8192); }
;       }
;       const char* sa = smem + (st & 1) * 65536 + (wr * 64 + fr) * 128;
;       const char* sb = smem + (st & 1) * 65536 + 32768 + (wc * 128 + fr) * 128;
;       if constexpr (THIN) {
;         if (wc == 0) {
; #pragma unroll
;           for (int ks = 0; ks < 2; ++ks) {
;             bf16x8 af[4], bf[2];
; #pragma unroll
;             for (int m = 0; m < 4; ++m) af[m] = *(const bf16x8*)(sa + m * 2048 + (((ks * 4 + fq) ^ swz) << 4));
; #pragma unroll
;             for (int n = 0; n < 2; ++n) bf[n] = *(const bf16x8*)(sb + n * 2048 + (((ks * 4 + fq) ^ swz) << 4));
; #pragma unroll
;             for (int m = 0; m < 4; ++m)
; #pragma unroll
;               for (int n = 0; n < 2; ++n)
;                 acc[m][n] = SWAP ? __builtin_amdgcn_mfma_f32_16x16x32_bf16(bf[n], af[m], acc[m][n], 0, 0, 0)
;                                  : __builtin_amdgcn_mfma_f32_16x16x32_bf16(af[m], bf[n], acc[m][n], 0, 0, 0);
;           }
;         }
;       } else {
;       bf16x8 afA[4], afB[4], bfb[2][2];
; #pragma unroll
;       for (int m = 0; m < 4; ++m) afA[m] = *(const bf16x8*)(sa + m * 2048 + ((fq ^ swz) << 4));
; #pragma unroll
;       for (int n = 0; n < 2; ++n) bfb[0][n] = *(const bf16x8*)(sb + n * 2048 + ((fq ^ swz) << 4));
; #pragma unroll
;       for (int gq = 0; gq < 8; ++gq) {
;         const int ks = gq >> 2, nh = gq & 3;
;         if (gq < 7) {
;           const int ks2 = (gq + 1) >> 2, nh2 = (gq + 1) & 3;
; #pragma unroll
;           for (int n = 0; n < 2; ++n) bfb[(gq + 1) & 1][n] = *(const bf16x8*)(sb + (nh2 * 2 + n) * 2048 + (((ks2 * 4 + fq) ^ swz) << 4));
;         }
;         if (gq == 3) {
; #pragma unroll
;           for (int m = 0; m < 4; ++m) afB[m] = *(const bf16x8*)(sa + m * 2048 + (((4 + fq) ^ swz) << 4));
;         }
;         __builtin_amdgcn_sched_barrier(0);
; #pragma unroll
	v_lshl_add_u64 v[146:147], v[132:133], 1, s[28:29]
	global_load_lds_dwordx4 v[146:147], off
	v_lshl_add_u64 v[146:147], v[10:11], 0, s[40:41]
	s_mov_b32 m0, s15
	v_add_u32_e32 v132, 0x80, v4
	global_load_lds_dwordx4 v[146:147], off
	v_lshl_add_u64 v[146:147], v[132:133], 1, s[28:29]
	s_mov_b32 m0, s14
	v_add_u32_e32 v132, 0x80, v6
	global_load_lds_dwordx4 v[146:147], off
	v_lshl_add_u64 v[146:147], v[12:13], 0, s[40:41]
	s_mov_b32 m0, s17
	v_mfma_f32_16x16x32_bf16 v[110:113], v[186:189], v[182:185], v[202:205]
	global_load_lds_dwordx4 v[146:147], off
	v_lshl_add_u64 v[146:147], v[132:133], 1, s[28:29]
	s_mov_b32 m0, s16
	v_add_u32_e32 v132, 0x80, v8
	global_load_lds_dwordx4 v[146:147], off
	v_lshl_add_u64 v[146:147], v[14:15], 0, s[40:41]
	s_mov_b32 m0, s19
	v_mfma_f32_16x16x32_bf16 v[18:21], v[186:189], v[214:217], v[18:21]
	global_load_lds_dwordx4 v[146:147], off
	v_lshl_add_u64 v[146:147], v[132:133], 1, s[28:29]
	s_mov_b32 m0, s18
	v_mfma_f32_16x16x32_bf16 v[142:145], v[190:193], v[182:185], v[206:209]
	global_load_lds_dwordx4 v[146:147], off
	v_lshl_add_u64 v[146:147], v[16:17], 0, s[40:41]
	s_mov_b32 m0, s20
	v_mfma_f32_16x16x32_bf16 v[22:25], v[190:193], v[214:217], v[22:25]
	global_load_lds_dwordx4 v[146:147], off
	v_mfma_f32_16x16x32_bf16 v[186:189], v[194:197], v[182:185], v[210:213]
	v_mfma_f32_16x16x32_bf16 v[26:29], v[194:197], v[214:217], v[26:29]
	v_mfma_f32_16x16x32_bf16 v[106:109], v[198:201], v[182:185], v[106:109]
	ds_read_b128 v[182:185], v178
	ds_read_b128 v[190:193], v178 offset:2048
	ds_read_b128 v[194:197], v178 offset:4096
	ds_read_b128 v[202:205], v178 offset:6144
	ds_read_b128 v[206:209], v179
	ds_read_b128 v[210:213], v179 offset:2048
	ds_read_b128 v[218:221], v179 offset:4096
	ds_read_b128 v[222:225], v179 offset:6144
	v_mfma_f32_16x16x32_bf16 v[30:33], v[198:201], v[214:217], v[30:33]
	s_waitcnt lgkmcnt(0)
	v_mfma_f32_16x16x32_bf16 v[50:53], v[182:185], v[206:209], v[50:53]
	v_mfma_f32_16x16x32_bf16 v[58:61], v[190:193], v[206:209], v[58:61]
	v_mfma_f32_16x16x32_bf16 v[66:69], v[194:197], v[206:209], v[66:69]
	v_mfma_f32_16x16x32_bf16 v[34:37], v[202:205], v[206:209], v[34:37]
	ds_read_b128 v[198:201], v179 offset:8192
	ds_read_b128 v[206:209], v179 offset:10240
	v_mfma_f32_16x16x32_bf16 v[54:57], v[182:185], v[210:213], v[54:57]
	v_mfma_f32_16x16x32_bf16 v[62:65], v[190:193], v[210:213], v[62:65]
	v_mfma_f32_16x16x32_bf16 v[70:73], v[194:197], v[210:213], v[70:73]
	v_mfma_f32_16x16x32_bf16 v[38:41], v[202:205], v[210:213], v[38:41]
	ds_read_b128 v[210:213], v179 offset:12288
	ds_read_b128 v[214:217], v179 offset:14336
	v_mfma_f32_16x16x32_bf16 v[82:85], v[182:185], v[218:221], v[82:85]
	v_mfma_f32_16x16x32_bf16 v[86:89], v[182:185], v[222:225], v[86:89]
	v_mfma_f32_16x16x32_bf16 v[90:93], v[190:193], v[218:221], v[90:93]
	v_mfma_f32_16x16x32_bf16 v[94:97], v[190:193], v[222:225], v[94:97]
	v_mfma_f32_16x16x32_bf16 v[98:101], v[194:197], v[218:221], v[98:101]
	v_mfma_f32_16x16x32_bf16 v[102:105], v[194:197], v[222:225], v[102:105]
	v_mfma_f32_16x16x32_bf16 v[42:45], v[202:205], v[218:221], v[42:45]
	v_mfma_f32_16x16x32_bf16 v[46:49], v[202:205], v[222:225], v[46:49]
	s_waitcnt lgkmcnt(0)
	v_mfma_f32_16x16x32_bf16 v[114:117], v[182:185], v[198:201], v[114:117]
	ds_read_b128 v[218:221], v180
	ds_read_b128 v[222:225], v180 offset:2048
	v_mfma_f32_16x16x32_bf16 v[122:125], v[190:193], v[198:201], v[122:125]
	v_mfma_f32_16x16x32_bf16 v[134:137], v[194:197], v[198:201], v[134:137]
	v_mfma_f32_16x16x32_bf16 v[74:77], v[202:205], v[198:201], v[74:77]
	ds_read_b128 v[198:201], v181
	ds_read_b128 v[226:229], v181 offset:2048
	ds_read_b128 v[230:233], v181 offset:4096
	ds_read_b128 v[234:237], v181 offset:6144
	v_mfma_f32_16x16x32_bf16 v[118:121], v[182:185], v[206:209], v[118:121]
	v_mfma_f32_16x16x32_bf16 v[126:129], v[190:193], v[206:209], v[126:129]
	v_mfma_f32_16x16x32_bf16 v[138:141], v[194:197], v[206:209], v[138:141]
	v_mfma_f32_16x16x32_bf16 v[78:81], v[202:205], v[206:209], v[78:81]
	v_mfma_f32_16x16x32_bf16 v[110:113], v[182:185], v[210:213], v[110:113]
	v_mfma_f32_16x16x32_bf16 v[18:21], v[182:185], v[214:217], v[18:21]
	v_mfma_f32_16x16x32_bf16 v[142:145], v[190:193], v[210:213], v[142:145]
	v_mfma_f32_16x16x32_bf16 v[22:25], v[190:193], v[214:217], v[22:25]
	v_mfma_f32_16x16x32_bf16 v[182:185], v[194:197], v[210:213], v[186:189]
	s_nop 2
	ds_read_b128 v[186:189], v180 offset:4096
	ds_read_b128 v[190:193], v180 offset:6144
	v_mfma_f32_16x16x32_bf16 v[26:29], v[194:197], v[214:217], v[26:29]
	v_mfma_f32_16x16x32_bf16 v[106:109], v[202:205], v[210:213], v[106:109]
	v_mfma_f32_16x16x32_bf16 v[30:33], v[202:205], v[214:217], v[30:33]
	ds_read_b128 v[194:197], v180 offset:8192
	ds_read_b128 v[202:205], v180 offset:10240
	s_waitcnt lgkmcnt(0)
	v_mfma_f32_16x16x32_bf16 v[50:53], v[198:201], v[218:221], v[50:53]
	v_mfma_f32_16x16x32_bf16 v[54:57], v[198:201], v[222:225], v[54:57]
	v_mfma_f32_16x16x32_bf16 v[58:61], v[226:229], v[218:221], v[58:61]
	v_mfma_f32_16x16x32_bf16 v[62:65], v[226:229], v[222:225], v[62:65]
	v_mfma_f32_16x16x32_bf16 v[66:69], v[230:233], v[218:221], v[66:69]
	v_mfma_f32_16x16x32_bf16 v[70:73], v[230:233], v[222:225], v[70:73]
	v_mfma_f32_16x16x32_bf16 v[34:37], v[234:237], v[218:221], v[34:37]
	v_mfma_f32_16x16x32_bf16 v[38:41], v[234:237], v[222:225], v[38:41]
	v_mfma_f32_16x16x32_bf16 v[82:85], v[198:201], v[186:189], v[82:85]
	v_mfma_f32_16x16x32_bf16 v[90:93], v[226:229], v[186:189], v[90:93]
	v_mfma_f32_16x16x32_bf16 v[98:101], v[230:233], v[186:189], v[98:101]
	v_mfma_f32_16x16x32_bf16 v[42:45], v[234:237], v[186:189], v[42:45]
	ds_read_b128 v[186:189], v180 offset:12288
	ds_read_b128 v[206:209], v180 offset:14336
	v_mfma_f32_16x16x32_bf16 v[86:89], v[198:201], v[190:193], v[86:89]
	v_mfma_f32_16x16x32_bf16 v[94:97], v[226:229], v[190:193], v[94:97]
	v_mfma_f32_16x16x32_bf16 v[102:105], v[230:233], v[190:193], v[102:105]
	v_mfma_f32_16x16x32_bf16 v[46:49], v[234:237], v[190:193], v[46:49]
	v_mfma_f32_16x16x32_bf16 v[114:117], v[198:201], v[194:197], v[114:117]
	v_mfma_f32_16x16x32_bf16 v[118:121], v[198:201], v[202:205], v[118:121]
	v_mfma_f32_16x16x32_bf16 v[122:125], v[226:229], v[194:197], v[122:125]
	v_mfma_f32_16x16x32_bf16 v[126:129], v[226:229], v[202:205], v[126:129]
	v_mfma_f32_16x16x32_bf16 v[134:137], v[230:233], v[194:197], v[134:137]
	v_mfma_f32_16x16x32_bf16 v[138:141], v[230:233], v[202:205], v[138:141]
	v_mfma_f32_16x16x32_bf16 v[74:77], v[234:237], v[194:197], v[74:77]
	v_mfma_f32_16x16x32_bf16 v[78:81], v[234:237], v[202:205], v[78:81]
	v_add_u32_e32 v132, 0xc0, v2
	s_mov_b32 m0, s13
	s_waitcnt vmcnt(0)
	s_barrier
; template <bool SWAP, class Epi, bool THIN = false> ...
;     ...
;     for (int st = 0; st < ns; ++st) {
;       asm volatile("s_waitcnt vmcnt(0)" ::: "memory");
;       __builtin_amdgcn_s_barrier();
;       asm volatile("" ::: "memory");
;       if (st + 1 < ns) {
;         char* nb = smem + ((st + 1) & 1) * 65536;
;         const int ko = (st + 1) * 64;
; #pragma unroll
;         for (int i = 0; i < 4; ++i) { GLDS16(A + (size_t)(ap[i] + ko), nb + tid * 16 + i * 8192); GLDS16(Bt + (size_t)(bp[i] + ko), nb + 32768 + tid * 16 + i * 8192); }
;       }
;       const char* sa = smem + (st & 1) * 65536 + (wr * 64 + fr) * 128;
;       const char* sb = smem + (st & 1) * 65536 + 32768 + (wc * 128 + fr) * 128;
;       if constexpr (THIN) {
;         if (wc == 0) {
; #pragma unroll
;           for (int ks = 0; ks < 2; ++ks) {
;             bf16x8 af[4], bf[2];
; #pragma unroll
;             for (int m = 0; m < 4; ++m) af[m] = *(const bf16x8*)(sa + m * 2048 + (((ks * 4 + fq) ^ swz) << 4));
; #pragma unroll
;             for (int n = 0; n < 2; ++n) bf[n] = *(const bf16x8*)(sb + n * 2048 + (((ks * 4 + fq) ^ swz) << 4));
; #pragma unroll
;             for (int m = 0; m < 4; ++m)
; #pragma unroll
;               for (int n = 0; n < 2; ++n)
;                 acc[m][n] = SWAP ? __builtin_amdgcn_mfma_f32_16x16x32_bf16(bf[n], af[m], acc[m][n], 0, 0, 0)
;                                  : __builtin_amdgcn_mfma_f32_16x16x32_bf16(af[m], bf[n], acc[m][n], 0, 0, 0);
;           }
;         }
;       } else {
;       bf16x8 afA[4], afB[4], bfb[2][2];
; #pragma unroll
;       for (int m = 0; m < 4; ++m) afA[m] = *(const bf16x8*)(sa + m * 2048 + ((fq ^ swz) << 4));
; #pragma unroll
;       for (int n = 0; n < 2; ++n) bfb[0][n] = *(const bf16x8*)(sb + n * 2048 + ((fq ^ swz) << 4));
; #pragma unroll
;       for (int gq = 0; gq < 8; ++gq) {
;         const int ks = gq >> 2, nh = gq & 3;
;         if (gq < 7) {
;           const int ks2 = (gq + 1) >> 2, nh2 = (gq + 1) & 3;
; #pragma unroll
;           for (int n = 0; n < 2; ++n) bfb[(gq + 1) & 1][n] = *(const bf16x8*)(sb + (nh2 * 2 + n) * 2048 + (((ks2 * 4 + fq) ^ swz) << 4));
;         }
;         if (gq == 3) {
; #pragma unroll
;           for (int m = 0; m < 4; ++m) afB[m] = *(const bf16x8*)(sa + m * 2048 + (((4 + fq) ^ swz) << 4));
;         }
;         __builtin_amdgcn_sched_barrier(0);
; #pragma unroll
	v_lshl_add_u64 v[2:3], v[132:133], 1, s[28:29]
	global_load_lds_dwordx4 v[2:3], off
	v_lshl_add_u64 v[2:3], v[10:11], 0, s[42:43]
	s_mov_b32 m0, s8
	v_add_u32_e32 v132, 0xc0, v4
	global_load_lds_dwordx4 v[2:3], off
	v_lshl_add_u64 v[10:11], v[132:133], 1, s[28:29]
	s_mov_b32 m0, s7
	v_add_u32_e32 v132, 0xc0, v6
	global_load_lds_dwordx4 v[10:11], off
	v_lshl_add_u64 v[10:11], v[12:13], 0, s[42:43]
	s_mov_b32 m0, s6
	v_lshl_add_u64 v[6:7], v[132:133], 1, s[28:29]
	global_load_lds_dwordx4 v[10:11], off
	s_mov_b32 m0, s9
	v_add_u32_e32 v132, 0xc0, v8
	global_load_lds_dwordx4 v[6:7], off
	v_lshl_add_u64 v[6:7], v[14:15], 0, s[42:43]
	s_mov_b32 m0, s10
	s_waitcnt lgkmcnt(0)
	v_mfma_f32_16x16x32_bf16 v[110:113], v[198:201], v[186:189], v[110:113]
	global_load_lds_dwordx4 v[6:7], off
	v_lshl_add_u64 v[6:7], v[132:133], 1, s[28:29]
	s_mov_b32 m0, s11
	v_mfma_f32_16x16x32_bf16 v[18:21], v[198:201], v[206:209], v[18:21]
	global_load_lds_dwordx4 v[6:7], off
	v_lshl_add_u64 v[6:7], v[16:17], 0, s[42:43]
	s_mov_b32 m0, s12
	v_mfma_f32_16x16x32_bf16 v[142:145], v[226:229], v[186:189], v[142:145]
	global_load_lds_dwordx4 v[6:7], off
	v_mfma_f32_16x16x32_bf16 v[2:5], v[230:233], v[186:189], v[182:185]
	v_mfma_f32_16x16x32_bf16 v[6:9], v[234:237], v[186:189], v[106:109]
	ds_read_b128 v[10:13], v174
	ds_read_b128 v[14:17], v174 offset:2048
	s_nop 0
	ds_read_b128 v[106:109], v174 offset:4096
	ds_read_b128 v[182:185], v174 offset:6144
	ds_read_b128 v[186:189], v175 offset:32768
	ds_read_b128 v[190:193], v175 offset:34816
	ds_read_b128 v[194:197], v175 offset:36864
	ds_read_b128 v[198:201], v175 offset:38912
	v_mfma_f32_16x16x32_bf16 v[22:25], v[226:229], v[206:209], v[22:25]
	v_mfma_f32_16x16x32_bf16 v[26:29], v[230:233], v[206:209], v[26:29]
	v_mfma_f32_16x16x32_bf16 v[30:33], v[234:237], v[206:209], v[30:33]
	s_waitcnt lgkmcnt(0)
	v_mfma_f32_16x16x32_bf16 v[50:53], v[10:13], v[186:189], v[50:53]
	v_mfma_f32_16x16x32_bf16 v[58:61], v[14:17], v[186:189], v[58:61]
	v_mfma_f32_16x16x32_bf16 v[66:69], v[106:109], v[186:189], v[66:69]
	v_mfma_f32_16x16x32_bf16 v[34:37], v[182:185], v[186:189], v[34:37]
	ds_read_b128 v[186:189], v175 offset:40960
	ds_read_b128 v[202:205], v175 offset:43008
	v_mfma_f32_16x16x32_bf16 v[54:57], v[10:13], v[190:193], v[54:57]
	v_mfma_f32_16x16x32_bf16 v[62:65], v[14:17], v[190:193], v[62:65]
	v_mfma_f32_16x16x32_bf16 v[70:73], v[106:109], v[190:193], v[70:73]
	v_mfma_f32_16x16x32_bf16 v[38:41], v[182:185], v[190:193], v[38:41]
	v_mfma_f32_16x16x32_bf16 v[82:85], v[10:13], v[194:197], v[82:85]
	v_mfma_f32_16x16x32_bf16 v[90:93], v[14:17], v[194:197], v[90:93]
	v_mfma_f32_16x16x32_bf16 v[98:101], v[106:109], v[194:197], v[98:101]
	v_mfma_f32_16x16x32_bf16 v[42:45], v[182:185], v[194:197], v[42:45]
	ds_read_b128 v[190:193], v175 offset:45056
	ds_read_b128 v[194:197], v175 offset:47104
	v_mfma_f32_16x16x32_bf16 v[86:89], v[10:13], v[198:201], v[86:89]
	v_mfma_f32_16x16x32_bf16 v[94:97], v[14:17], v[198:201], v[94:97]
	v_mfma_f32_16x16x32_bf16 v[102:105], v[106:109], v[198:201], v[102:105]
	v_mfma_f32_16x16x32_bf16 v[46:49], v[182:185], v[198:201], v[46:49]
	s_waitcnt lgkmcnt(0)
	v_mfma_f32_16x16x32_bf16 v[114:117], v[10:13], v[186:189], v[114:117]
	ds_read_b128 v[198:201], v176 offset:32768
	ds_read_b128 v[206:209], v176 offset:34816
	v_mfma_f32_16x16x32_bf16 v[122:125], v[14:17], v[186:189], v[122:125]
	v_mfma_f32_16x16x32_bf16 v[134:137], v[106:109], v[186:189], v[134:137]
	v_mfma_f32_16x16x32_bf16 v[74:77], v[182:185], v[186:189], v[74:77]
	ds_read_b128 v[186:189], v177
	ds_read_b128 v[210:213], v177 offset:2048
	ds_read_b128 v[214:217], v177 offset:4096
	ds_read_b128 v[218:221], v177 offset:6144
	v_mfma_f32_16x16x32_bf16 v[118:121], v[10:13], v[202:205], v[118:121]
	v_mfma_f32_16x16x32_bf16 v[126:129], v[14:17], v[202:205], v[126:129]
	v_mfma_f32_16x16x32_bf16 v[138:141], v[106:109], v[202:205], v[138:141]
	v_mfma_f32_16x16x32_bf16 v[78:81], v[182:185], v[202:205], v[78:81]
	v_mfma_f32_16x16x32_bf16 v[110:113], v[10:13], v[190:193], v[110:113]
	v_mfma_f32_16x16x32_bf16 v[10:13], v[10:13], v[194:197], v[18:21]
	v_mfma_f32_16x16x32_bf16 v[18:21], v[14:17], v[190:193], v[142:145]
	v_mfma_f32_16x16x32_bf16 v[14:17], v[14:17], v[194:197], v[22:25]
	v_mfma_f32_16x16x32_bf16 v[2:5], v[106:109], v[190:193], v[2:5]
	v_mfma_f32_16x16x32_bf16 v[22:25], v[106:109], v[194:197], v[26:29]
	s_nop 2
	ds_read_b128 v[26:29], v176 offset:36864
	ds_read_b128 v[106:109], v176 offset:38912
	v_mfma_f32_16x16x32_bf16 v[6:9], v[182:185], v[190:193], v[6:9]
	v_mfma_f32_16x16x32_bf16 v[30:33], v[182:185], v[194:197], v[30:33]
	ds_read_b128 v[142:145], v176 offset:40960
	ds_read_b128 v[182:185], v176 offset:43008
	s_waitcnt lgkmcnt(0)
	v_mfma_f32_16x16x32_bf16 v[50:53], v[186:189], v[198:201], v[50:53]
	v_mfma_f32_16x16x32_bf16 v[54:57], v[186:189], v[206:209], v[54:57]
	v_mfma_f32_16x16x32_bf16 v[58:61], v[210:213], v[198:201], v[58:61]
	v_mfma_f32_16x16x32_bf16 v[62:65], v[210:213], v[206:209], v[62:65]
	v_mfma_f32_16x16x32_bf16 v[66:69], v[214:217], v[198:201], v[66:69]
	v_mfma_f32_16x16x32_bf16 v[70:73], v[214:217], v[206:209], v[70:73]
	v_mfma_f32_16x16x32_bf16 v[34:37], v[218:221], v[198:201], v[34:37]
	v_mfma_f32_16x16x32_bf16 v[38:41], v[218:221], v[206:209], v[38:41]
	v_mfma_f32_16x16x32_bf16 v[82:85], v[186:189], v[26:29], v[82:85]
	v_mfma_f32_16x16x32_bf16 v[90:93], v[210:213], v[26:29], v[90:93]
	v_mfma_f32_16x16x32_bf16 v[98:101], v[214:217], v[26:29], v[98:101]
	v_mfma_f32_16x16x32_bf16 v[26:29], v[218:221], v[26:29], v[42:45]
	s_nop 2
	ds_read_b128 v[42:45], v176 offset:45056
	ds_read_b128 v[190:193], v176 offset:47104
	v_mfma_f32_16x16x32_bf16 v[86:89], v[186:189], v[106:109], v[86:89]
	v_mfma_f32_16x16x32_bf16 v[94:97], v[210:213], v[106:109], v[94:97]
	v_mfma_f32_16x16x32_bf16 v[102:105], v[214:217], v[106:109], v[102:105]
	v_mfma_f32_16x16x32_bf16 v[46:49], v[218:221], v[106:109], v[46:49]
	v_mfma_f32_16x16x32_bf16 v[106:109], v[186:189], v[142:145], v[114:117]
	v_mfma_f32_16x16x32_bf16 v[114:117], v[186:189], v[182:185], v[118:121]
	v_mfma_f32_16x16x32_bf16 v[118:121], v[210:213], v[142:145], v[122:125]
	v_mfma_f32_16x16x32_bf16 v[122:125], v[210:213], v[182:185], v[126:129]
	v_mfma_f32_16x16x32_bf16 v[126:129], v[214:217], v[142:145], v[134:137]
	v_mfma_f32_16x16x32_bf16 v[134:137], v[214:217], v[182:185], v[138:141]
	v_mfma_f32_16x16x32_bf16 v[74:77], v[218:221], v[142:145], v[74:77]
	v_mfma_f32_16x16x32_bf16 v[78:81], v[218:221], v[182:185], v[78:81]
	s_waitcnt vmcnt(0)
	s_barrier
; template <bool SWAP, class Epi, bool THIN = false> ...
;     ...
;       bf16x8 afA[4], afB[4], bfb[2][2];
; #pragma unroll
;       for (int m = 0; m < 4; ++m) afA[m] = *(const bf16x8*)(sa + m * 2048 + ((fq ^ swz) << 4));
; #pragma unroll
;       for (int n = 0; n < 2; ++n) bfb[0][n] = *(const bf16x8*)(sb + n * 2048 + ((fq ^ swz) << 4));
; #pragma unroll
;       for (int gq = 0; gq < 8; ++gq) {
;         const int ks = gq >> 2, nh = gq & 3;
;         if (gq < 7) {
;           const int ks2 = (gq + 1) >> 2, nh2 = (gq + 1) & 3;
; #pragma unroll
;           for (int n = 0; n < 2; ++n) bfb[(gq + 1) & 1][n] = *(const bf16x8*)(sb + (nh2 * 2 + n) * 2048 + (((ks2 * 4 + fq) ^ swz) << 4));
;         }
;         if (gq == 3) {
; #pragma unroll
;           for (int m = 0; m < 4; ++m) afB[m] = *(const bf16x8*)(sa + m * 2048 + (((4 + fq) ^ swz) << 4));
;         }
;         __builtin_amdgcn_sched_barrier(0);
; #pragma unroll
;         for (int m = 0; m < 4; ++m)
; #pragma unroll
;           for (int n = 0; n < 2; ++n) {
;             const bf16x8 av = ks ? afB[m] : afA[m];
;             acc[m][nh * 2 + n] = SWAP ? __builtin_amdgcn_mfma_f32_16x16x32_bf16(bfb[gq & 1][n], av, acc[m][nh * 2 + n], 0, 0, 0)
;                                       : __builtin_amdgcn_mfma_f32_16x16x32_bf16(av, bfb[gq & 1][n], acc[m][nh * 2 + n], 0, 0, 0);
;           }
;       }
;       }
;     }
;     __syncthreads();
	s_waitcnt lgkmcnt(0)
	v_mfma_f32_16x16x32_bf16 v[110:113], v[186:189], v[42:45], v[110:113]
	v_mfma_f32_16x16x32_bf16 v[10:13], v[186:189], v[190:193], v[10:13]
	ds_read_b128 v[138:141], v178
	ds_read_b128 v[142:145], v178 offset:2048
	ds_read_b128 v[182:185], v178 offset:4096
	ds_read_b128 v[186:189], v178 offset:6144
	v_mfma_f32_16x16x32_bf16 v[18:21], v[210:213], v[42:45], v[18:21]
	v_mfma_f32_16x16x32_bf16 v[2:5], v[214:217], v[42:45], v[2:5]
	v_mfma_f32_16x16x32_bf16 v[6:9], v[218:221], v[42:45], v[6:9]
	ds_read_b128 v[42:45], v179
	ds_read_b128 v[194:197], v179 offset:2048
	ds_read_b128 v[198:201], v179 offset:4096
	ds_read_b128 v[202:205], v179 offset:6144
	v_mfma_f32_16x16x32_bf16 v[14:17], v[210:213], v[190:193], v[14:17]
	v_mfma_f32_16x16x32_bf16 v[22:25], v[214:217], v[190:193], v[22:25]
	v_mfma_f32_16x16x32_bf16 v[30:33], v[218:221], v[190:193], v[30:33]
	s_waitcnt lgkmcnt(0)
	v_mfma_f32_16x16x32_bf16 v[50:53], v[138:141], v[42:45], v[50:53]
	v_mfma_f32_16x16x32_bf16 v[58:61], v[142:145], v[42:45], v[58:61]
	v_mfma_f32_16x16x32_bf16 v[66:69], v[182:185], v[42:45], v[66:69]
	v_mfma_f32_16x16x32_bf16 v[34:37], v[186:189], v[42:45], v[34:37]
	ds_read_b128 v[42:45], v179 offset:8192
	ds_read_b128 v[190:193], v179 offset:10240
	v_mfma_f32_16x16x32_bf16 v[54:57], v[138:141], v[194:197], v[54:57]
	v_mfma_f32_16x16x32_bf16 v[62:65], v[142:145], v[194:197], v[62:65]
	v_mfma_f32_16x16x32_bf16 v[70:73], v[182:185], v[194:197], v[70:73]
	v_mfma_f32_16x16x32_bf16 v[38:41], v[186:189], v[194:197], v[38:41]
	v_mfma_f32_16x16x32_bf16 v[82:85], v[138:141], v[198:201], v[82:85]
	v_mfma_f32_16x16x32_bf16 v[194:197], v[142:145], v[198:201], v[90:93]
	v_mfma_f32_16x16x32_bf16 v[98:101], v[182:185], v[198:201], v[98:101]
	v_mfma_f32_16x16x32_bf16 v[198:201], v[186:189], v[198:201], v[26:29]
	s_nop 2
	ds_read_b128 v[26:29], v179 offset:12288
	ds_read_b128 v[90:93], v179 offset:14336
	v_mfma_f32_16x16x32_bf16 v[86:89], v[138:141], v[202:205], v[86:89]
	v_mfma_f32_16x16x32_bf16 v[102:105], v[182:185], v[202:205], v[102:105]
	v_mfma_f32_16x16x32_bf16 v[46:49], v[186:189], v[202:205], v[46:49]
	v_mfma_f32_16x16x32_bf16 v[206:209], v[142:145], v[202:205], v[94:97]
	s_waitcnt lgkmcnt(0)
	v_mfma_f32_16x16x32_bf16 v[202:205], v[138:141], v[190:193], v[114:117]
	v_mfma_f32_16x16x32_bf16 v[210:213], v[142:145], v[42:45], v[118:121]
	s_nop 1
	ds_read_b128 v[114:117], v180
	ds_read_b128 v[118:121], v180 offset:2048
	ds_read_b128 v[226:229], v181
	ds_read_b128 v[230:233], v181 offset:2048
	ds_read_b128 v[234:237], v181 offset:4096
	ds_read_b128 v[238:241], v181 offset:6144
	v_mfma_f32_16x16x32_bf16 v[106:109], v[138:141], v[42:45], v[106:109]
	v_mfma_f32_16x16x32_bf16 v[134:137], v[182:185], v[190:193], v[134:137]
	v_mfma_f32_16x16x32_bf16 v[214:217], v[142:145], v[190:193], v[122:125]
	v_mfma_f32_16x16x32_bf16 v[218:221], v[182:185], v[42:45], v[126:129]
	v_mfma_f32_16x16x32_bf16 v[222:225], v[186:189], v[42:45], v[74:77]
	v_mfma_f32_16x16x32_bf16 v[190:193], v[186:189], v[190:193], v[78:81]
	v_mfma_f32_16x16x32_bf16 v[242:245], v[138:141], v[26:29], v[110:113]
	v_mfma_f32_16x16x32_bf16 v[138:141], v[138:141], v[90:93], v[10:13]
	v_mfma_f32_16x16x32_bf16 v[246:249], v[142:145], v[26:29], v[18:21]
	v_mfma_f32_16x16x32_bf16 v[142:145], v[142:145], v[90:93], v[14:17]
	s_nop 0
	ds_read_b128 v[10:13], v180 offset:4096
	s_nop 0
	ds_read_b128 v[14:17], v180 offset:6144
	v_mfma_f32_16x16x32_bf16 v[2:5], v[182:185], v[26:29], v[2:5]
	v_mfma_f32_16x16x32_bf16 v[6:9], v[186:189], v[26:29], v[6:9]
	v_mfma_f32_16x16x32_bf16 v[182:185], v[182:185], v[90:93], v[22:25]
	v_mfma_f32_16x16x32_bf16 v[186:189], v[186:189], v[90:93], v[30:33]
	s_waitcnt lgkmcnt(0)
	v_mfma_f32_16x16x32_bf16 v[90:93], v[230:233], v[118:121], v[62:65]
	v_mfma_f32_16x16x32_bf16 v[62:65], v[234:237], v[114:117], v[66:69]
	v_mfma_f32_16x16x32_bf16 v[30:33], v[238:241], v[114:117], v[34:37]
	s_nop 2
	ds_read_b128 v[34:37], v180 offset:8192
	ds_read_b128 v[66:69], v180 offset:10240
	v_mfma_f32_16x16x32_bf16 v[126:129], v[226:229], v[114:117], v[50:53]
	v_mfma_f32_16x16x32_bf16 v[122:125], v[226:229], v[118:121], v[54:57]
	v_mfma_f32_16x16x32_bf16 v[94:97], v[230:233], v[114:117], v[58:61]
	v_mfma_f32_16x16x32_bf16 v[58:61], v[234:237], v[118:121], v[70:73]
	v_mfma_f32_16x16x32_bf16 v[26:29], v[238:241], v[118:121], v[38:41]
	v_mfma_f32_16x16x32_bf16 v[114:117], v[226:229], v[14:17], v[86:89]
	v_mfma_f32_16x16x32_bf16 v[86:89], v[230:233], v[10:13], v[194:197]
	v_mfma_f32_16x16x32_bf16 v[22:25], v[238:241], v[10:13], v[198:201]
	s_nop 1
	ds_read_b128 v[194:197], v180 offset:12288
	ds_read_b128 v[198:201], v180 offset:14336
	v_mfma_f32_16x16x32_bf16 v[118:121], v[226:229], v[10:13], v[82:85]
	v_mfma_f32_16x16x32_bf16 v[82:85], v[230:233], v[14:17], v[206:209]
	v_mfma_f32_16x16x32_bf16 v[54:57], v[234:237], v[10:13], v[98:101]
	v_mfma_f32_16x16x32_bf16 v[50:53], v[234:237], v[14:17], v[102:105]
	v_mfma_f32_16x16x32_bf16 v[18:21], v[238:241], v[14:17], v[46:49]
	s_waitcnt lgkmcnt(0)
	v_mfma_f32_16x16x32_bf16 v[110:113], v[226:229], v[34:37], v[106:109]
	v_mfma_f32_16x16x32_bf16 v[106:109], v[226:229], v[66:69], v[202:205]
	v_mfma_f32_16x16x32_bf16 v[78:81], v[230:233], v[34:37], v[210:213]
	v_mfma_f32_16x16x32_bf16 v[74:77], v[230:233], v[66:69], v[214:217]
	v_mfma_f32_16x16x32_bf16 v[46:49], v[234:237], v[34:37], v[218:221]
	v_mfma_f32_16x16x32_bf16 v[42:45], v[234:237], v[66:69], v[134:137]
	v_mfma_f32_16x16x32_bf16 v[14:17], v[238:241], v[34:37], v[222:225]
	v_mfma_f32_16x16x32_bf16 v[10:13], v[238:241], v[66:69], v[190:193]
	v_mov_b32_e32 v132, v1
	s_waitcnt vmcnt(0)
	s_barrier
; __device__ __forceinline__ int get_tid512() { int t = threadIdx.x; asm volatile("" : "+v"(t)); return t; }
; __device__ __forceinline__ unsigned pack2(float a, float b) { unsigned r; asm("v_cvt_pk_bf16_f32 %0, %1, %2" : "=v"(r) : "v"(a), "v"(b)); return r; }
;   __device__ __forceinline__ void r4(int g, int rig, int col, f32x4 v) const {
;     const size_t row = (size_t)g * 2304 + rig;
;     const f32x4 t = *(const f32x4*)(part + row) + *(const f32x4*)(part + 18432 + row);
;     f32x4 s;
; #pragma unroll
;     for (int j = 0; j < 4; ++j) s[j] = rsqrtf(t[j] * (1.0f / 256.0f) + 1e-6f);
;     uint2 u; u.x = pack2(v[0] * s[0], v[1] * s[1]); u.y = pack2(v[2] * s[2], v[3] * s[3]);
;     *(uint2*)(out + ((size_t)g * 1024 + col) * 2304 + rig) = u;
;   }
; template <bool SWAP, class Epi, bool THIN = false> ...
;     ...
;     const int te = get_tid512();
;     const int fr_e = te & 15, fq_e = (te & 63) >> 4, wr_e = te >> 7, wc_e = (te >> 6) & 1;
;     const int sub = 2 * mt + (wr_e >> 1);
;     const int g = sub / tpg, ti = sub - g * tpg;
;     const int rig0 = ti * step - halo;
;     const int rw = (wr_e & 1) * 64;
	v_mfma_f32_16x16x32_bf16 v[66:69], v[230:233], v[198:201], v[142:145]
	v_ashrrev_i32_e32 v34, 8, v132
	v_add_u32_e32 v34, s5, v34
	v_mul_hi_i32 v35, v34, s51
	v_lshrrev_b32_e32 v36, 31, v35
	v_ashrrev_i32_e32 v35, 2, v35
	v_add_u32_e32 v144, v35, v36
	v_mul_lo_u32 v35, v144, s56
	v_mfma_f32_16x16x32_bf16 v[38:41], v[234:237], v[194:197], v[2:5]
	v_add_lshl_u32 v135, v35, v34, 7
	v_and_b32_e32 v134, 15, v132
	v_ashrrev_i32_e32 v145, 31, v144
	v_lshrrev_b32_e32 v2, 1, v132
	v_lshrrev_b32_e32 v3, 2, v132
	v_and_b32_e32 v2, 64, v2
	v_and_b32_e32 v3, 12, v3
	v_or3_b32 v142, v135, v2, v3
	v_lshlrev_b32_e32 v2, 1, v132
	v_and_b32_e32 v2, 0x80, v2
	v_mfma_f32_16x16x32_bf16 v[102:105], v[226:229], v[194:197], v[242:245]
	v_ashrrev_i32_e32 v143, 31, v142
	v_mfma_f32_16x16x32_bf16 v[98:101], v[226:229], v[198:201], v[138:141]
	v_mfma_f32_16x16x32_bf16 v[70:73], v[230:233], v[194:197], v[246:249]
	s_nop 1
	v_or3_b32 v140, v134, v2, s4
	v_mad_i64_i32 v[136:137], s[4:5], v144, s57, v[142:143]
	v_mfma_f32_16x16x32_bf16 v[34:37], v[234:237], v[198:201], v[182:185]
	v_lshlrev_b64 v[136:137], 2, v[136:137]
	v_lshlrev_b64 v[134:135], 10, v[144:145]
	v_lshl_add_u64 v[138:139], s[26:27], 0, v[136:137]
	v_mfma_f32_16x16x32_bf16 v[6:9], v[238:241], v[194:197], v[6:9]
	v_lshl_add_u64 v[146:147], s[36:37], 0, v[136:137]
	v_lshl_add_u64 v[136:137], v[142:143], 1, s[30:31]
	v_cmp_gt_i32_e32 vcc, s59, v140
	v_mfma_f32_16x16x32_bf16 v[2:5], v[238:241], v[198:201], v[186:189]
	v_ashrrev_i32_e32 v141, 31, v140
	global_load_dwordx4 v[182:185], v[138:139], off
	global_load_dwordx4 v[186:189], v[146:147], off
	global_load_dwordx4 v[190:193], v[138:139], off offset:64
	global_load_dwordx4 v[194:197], v[146:147], off offset:64
	global_load_dwordx4 v[198:201], v[138:139], off offset:128
	global_load_dwordx4 v[202:205], v[146:147], off offset:128
	global_load_dwordx4 v[206:209], v[138:139], off offset:192
	global_load_dwordx4 v[210:213], v[146:147], off offset:192
	v_mov_b64_e32 v[222:223], s[48:49]
	v_bfe_u32 v220, v1, 4, 1
	v_mul_u32_u24_e32 v220, 24, v220
	v_mov_b32_e32 v221, 0
	s_waitcnt vmcnt(0)
	v_pk_add_f32 v[182:183], v[182:183], v[186:187]
	v_pk_add_f32 v[184:185], v[184:185], v[188:189]
	v_pk_fma_f32 v[182:183], v[182:183], s[44:45], v[222:223] op_sel_hi:[1,0,0]
	v_pk_fma_f32 v[184:185], v[184:185], s[44:45], v[222:223] op_sel_hi:[1,0,0]
	v_mul_f32_e32 v186, 0x4b800000, v182
	v_cmp_gt_f32_e32 vcc, s60, v182
	s_nop 1
	v_cndmask_b32_e32 v182, v182, v186, vcc
	v_rsq_f32_e32 v182, v182
	s_nop 1
	v_mul_f32_e32 v186, 0x45800000, v182
	v_cndmask_b32_e32 v182, v182, v186, vcc
	v_mul_f32_e32 v187, 0x4b800000, v183
	v_cmp_gt_f32_e32 vcc, s60, v183
	s_nop 1
	v_cndmask_b32_e32 v183, v183, v187, vcc
	v_rsq_f32_e32 v183, v183
	s_nop 1
	v_mul_f32_e32 v187, 0x45800000, v183
	v_cndmask_b32_e32 v183, v183, v187, vcc
	v_mul_f32_e32 v188, 0x4b800000, v184
	v_cmp_gt_f32_e32 vcc, s60, v184
	s_nop 1
	v_cndmask_b32_e32 v184, v184, v188, vcc
	v_rsq_f32_e32 v184, v184
	s_nop 1
	v_mul_f32_e32 v188, 0x45800000, v184
	v_cndmask_b32_e32 v184, v184, v188, vcc
	v_mul_f32_e32 v189, 0x4b800000, v185
	v_cmp_gt_f32_e32 vcc, s60, v185
	s_nop 1
	v_cndmask_b32_e32 v185, v185, v189, vcc
	v_rsq_f32_e32 v185, v185
	s_nop 1
	v_mul_f32_e32 v189, 0x45800000, v185
	v_cndmask_b32_e32 v185, v185, v189, vcc
	v_pk_add_f32 v[190:191], v[190:191], v[194:195]
	v_pk_add_f32 v[192:193], v[192:193], v[196:197]
	v_pk_fma_f32 v[190:191], v[190:191], s[44:45], v[222:223] op_sel_hi:[1,0,0]
	v_pk_fma_f32 v[192:193], v[192:193], s[44:45], v[222:223] op_sel_hi:[1,0,0]
	v_mul_f32_e32 v194, 0x4b800000, v190
	v_cmp_gt_f32_e32 vcc, s60, v190
	s_nop 1
	v_cndmask_b32_e32 v190, v190, v194, vcc
	v_rsq_f32_e32 v190, v190
	s_nop 1
	v_mul_f32_e32 v194, 0x45800000, v190
	v_cndmask_b32_e32 v190, v190, v194, vcc
	v_mul_f32_e32 v195, 0x4b800000, v191
	v_cmp_gt_f32_e32 vcc, s60, v191
	s_nop 1
	v_cndmask_b32_e32 v191, v191, v195, vcc
	v_rsq_f32_e32 v191, v191
	s_nop 1
	v_mul_f32_e32 v195, 0x45800000, v191
	v_cndmask_b32_e32 v191, v191, v195, vcc
	v_mul_f32_e32 v196, 0x4b800000, v192
	v_cmp_gt_f32_e32 vcc, s60, v192
	s_nop 1
	v_cndmask_b32_e32 v192, v192, v196, vcc
	v_rsq_f32_e32 v192, v192
	s_nop 1
	v_mul_f32_e32 v196, 0x45800000, v192
	v_cndmask_b32_e32 v192, v192, v196, vcc
	v_mul_f32_e32 v197, 0x4b800000, v193
	v_cmp_gt_f32_e32 vcc, s60, v193
	s_nop 1
	v_cndmask_b32_e32 v193, v193, v197, vcc
	v_rsq_f32_e32 v193, v193
	s_nop 1
	v_mul_f32_e32 v197, 0x45800000, v193
	v_cndmask_b32_e32 v193, v193, v197, vcc
	v_pk_add_f32 v[198:199], v[198:199], v[202:203]
	v_pk_add_f32 v[200:201], v[200:201], v[204:205]
	v_pk_fma_f32 v[198:199], v[198:199], s[44:45], v[222:223] op_sel_hi:[1,0,0]
	v_pk_fma_f32 v[200:201], v[200:201], s[44:45], v[222:223] op_sel_hi:[1,0,0]
	v_mul_f32_e32 v202, 0x4b800000, v198
	v_cmp_gt_f32_e32 vcc, s60, v198
	s_nop 1
	v_cndmask_b32_e32 v198, v198, v202, vcc
	v_rsq_f32_e32 v198, v198
	s_nop 1
	v_mul_f32_e32 v202, 0x45800000, v198
	v_cndmask_b32_e32 v198, v198, v202, vcc
	v_mul_f32_e32 v203, 0x4b800000, v199
	v_cmp_gt_f32_e32 vcc, s60, v199
	s_nop 1
	v_cndmask_b32_e32 v199, v199, v203, vcc
	v_rsq_f32_e32 v199, v199
	s_nop 1
	v_mul_f32_e32 v203, 0x45800000, v199
	v_cndmask_b32_e32 v199, v199, v203, vcc
	v_mul_f32_e32 v204, 0x4b800000, v200
	v_cmp_gt_f32_e32 vcc, s60, v200
	s_nop 1
	v_cndmask_b32_e32 v200, v200, v204, vcc
	v_rsq_f32_e32 v200, v200
	s_nop 1
	v_mul_f32_e32 v204, 0x45800000, v200
	v_cndmask_b32_e32 v200, v200, v204, vcc
	v_mul_f32_e32 v205, 0x4b800000, v201
	v_cmp_gt_f32_e32 vcc, s60, v201
	s_nop 1
	v_cndmask_b32_e32 v201, v201, v205, vcc
	v_rsq_f32_e32 v201, v201
	s_nop 1
	v_mul_f32_e32 v205, 0x45800000, v201
; __device__ __forceinline__ unsigned pack2(float a, float b) { unsigned r; asm("v_cvt_pk_bf16_f32 %0, %1, %2" : "=v"(r) : "v"(a), "v"(b)); return r; }
;   __device__ __forceinline__ void r4(int g, int rig, int col, f32x4 v) const {
;     const size_t row = (size_t)g * 2304 + rig;
;     const f32x4 t = *(const f32x4*)(part + row) + *(const f32x4*)(part + 18432 + row);
;     f32x4 s;
; #pragma unroll
;     for (int j = 0; j < 4; ++j) s[j] = rsqrtf(t[j] * (1.0f / 256.0f) + 1e-6f);
;     uint2 u; u.x = pack2(v[0] * s[0], v[1] * s[1]); u.y = pack2(v[2] * s[2], v[3] * s[3]);
;     *(uint2*)(out + ((size_t)g * 1024 + col) * 2304 + rig) = u;
;   }
; template <bool SWAP, class Epi, bool THIN = false> ...
;     ...
;     } else if constexpr (Epi::KIND == 1) {
; #pragma unroll
;       for (int m = 0; m < 4; ++m) {
;         const int rig = rig0 + rw + m * 16 + fq_e * 4;
; #pragma unroll
;         for (int n = 0; n < 8; ++n) {
;           const int col = nt * 256 + wc_e * 128 + n * 16 + fr_e;
;           if (col < N) epi.r4(g, rig, col, acc[m][n]);
;         }
;       }
	v_cndmask_b32_e32 v201, v201, v205, vcc
	v_pk_add_f32 v[206:207], v[206:207], v[210:211]
	v_pk_add_f32 v[208:209], v[208:209], v[212:213]
	v_pk_fma_f32 v[206:207], v[206:207], s[44:45], v[222:223] op_sel_hi:[1,0,0]
	v_pk_fma_f32 v[208:209], v[208:209], s[44:45], v[222:223] op_sel_hi:[1,0,0]
	v_mul_f32_e32 v210, 0x4b800000, v206
	v_cmp_gt_f32_e32 vcc, s60, v206
	s_nop 1
	v_cndmask_b32_e32 v206, v206, v210, vcc
	v_rsq_f32_e32 v206, v206
	s_nop 1
	v_mul_f32_e32 v210, 0x45800000, v206
	v_cndmask_b32_e32 v206, v206, v210, vcc
	v_mul_f32_e32 v211, 0x4b800000, v207
	v_cmp_gt_f32_e32 vcc, s60, v207
	s_nop 1
	v_cndmask_b32_e32 v207, v207, v211, vcc
	v_rsq_f32_e32 v207, v207
	s_nop 1
	v_mul_f32_e32 v211, 0x45800000, v207
	v_cndmask_b32_e32 v207, v207, v211, vcc
	v_mul_f32_e32 v212, 0x4b800000, v208
	v_cmp_gt_f32_e32 vcc, s60, v208
	s_nop 1
	v_cndmask_b32_e32 v208, v208, v212, vcc
	v_rsq_f32_e32 v208, v208
	s_nop 1
	v_mul_f32_e32 v212, 0x45800000, v208
	v_cndmask_b32_e32 v208, v208, v212, vcc
	v_mul_f32_e32 v213, 0x4b800000, v209
	v_cmp_gt_f32_e32 vcc, s60, v209
	s_nop 1
	v_cndmask_b32_e32 v209, v209, v213, vcc
	v_rsq_f32_e32 v209, v209
	s_nop 1
	v_mul_f32_e32 v213, 0x45800000, v209
	v_cndmask_b32_e32 v209, v209, v213, vcc
	v_lshl_add_u64 v[216:217], v[134:135], 0, v[140:141]
	v_mad_u64_u32 v[218:219], s[4:5], v216, s61, v[136:137]
	v_mad_i32_i24 v219, v217, s61, v219
	v_lshl_add_u64 v[218:219], v[218:219], 0, v[220:221]
	v_mul_f32_e32 v126, v126, v182
	v_mul_f32_e32 v127, v127, v183
	v_mul_f32_e32 v128, v128, v184
	v_mul_f32_e32 v129, v129, v185
	v_mul_f32_e32 v94, v94, v190
	v_mul_f32_e32 v95, v95, v191
	v_mul_f32_e32 v96, v96, v192
	v_mul_f32_e32 v97, v97, v193
	v_cvt_pk_bf16_f32 v126, v126, v127
	v_cvt_pk_bf16_f32 v127, v128, v129
	v_cvt_pk_bf16_f32 v128, v94, v95
	v_cvt_pk_bf16_f32 v129, v96, v97
	s_nop 1
	v_permlane16_swap_b32 v126, v128
	v_permlane16_swap_b32 v127, v129
	global_store_dwordx4 v[218:219], v[126:129], off
	v_mul_f32_e32 v62, v62, v198
	v_mul_f32_e32 v63, v63, v199
	v_mul_f32_e32 v64, v64, v200
	v_mul_f32_e32 v65, v65, v201
	v_mul_f32_e32 v30, v30, v206
	v_mul_f32_e32 v31, v31, v207
	v_mul_f32_e32 v32, v32, v208
	v_mul_f32_e32 v33, v33, v209
	v_cvt_pk_bf16_f32 v62, v62, v63
	v_cvt_pk_bf16_f32 v63, v64, v65
	v_cvt_pk_bf16_f32 v64, v30, v31
	v_cvt_pk_bf16_f32 v65, v32, v33
	s_nop 1
	v_permlane16_swap_b32 v62, v64
	v_permlane16_swap_b32 v63, v65
	global_store_dwordx4 v[218:219], v[62:65], off offset:64
	s_nop 1
	v_or_b32_e32 v214, 16, v140
	v_ashrrev_i32_e32 v215, 31, v214
	v_lshl_add_u64 v[216:217], v[134:135], 0, v[214:215]
	v_mad_u64_u32 v[218:219], s[4:5], v216, s61, v[136:137]
	v_mad_i32_i24 v219, v217, s61, v219
	v_lshl_add_u64 v[218:219], v[218:219], 0, v[220:221]
	v_mul_f32_e32 v122, v122, v182
	v_mul_f32_e32 v123, v123, v183
	v_mul_f32_e32 v124, v124, v184
	v_mul_f32_e32 v125, v125, v185
	v_mul_f32_e32 v90, v90, v190
	v_mul_f32_e32 v91, v91, v191
	v_mul_f32_e32 v92, v92, v192
	v_mul_f32_e32 v93, v93, v193
	v_cvt_pk_bf16_f32 v122, v122, v123
	v_cvt_pk_bf16_f32 v123, v124, v125
	v_cvt_pk_bf16_f32 v124, v90, v91
	v_cvt_pk_bf16_f32 v125, v92, v93
	s_nop 1
	v_permlane16_swap_b32 v122, v124
	v_permlane16_swap_b32 v123, v125
	global_store_dwordx4 v[218:219], v[122:125], off
	v_mul_f32_e32 v58, v58, v198
	v_mul_f32_e32 v59, v59, v199
	v_mul_f32_e32 v60, v60, v200
	v_mul_f32_e32 v61, v61, v201
	v_mul_f32_e32 v26, v26, v206
	v_mul_f32_e32 v27, v27, v207
	v_mul_f32_e32 v28, v28, v208
	v_mul_f32_e32 v29, v29, v209
	v_cvt_pk_bf16_f32 v58, v58, v59
	v_cvt_pk_bf16_f32 v59, v60, v61
	v_cvt_pk_bf16_f32 v60, v26, v27
	v_cvt_pk_bf16_f32 v61, v28, v29
	s_nop 1
	v_permlane16_swap_b32 v58, v60
	v_permlane16_swap_b32 v59, v61
	global_store_dwordx4 v[218:219], v[58:61], off offset:64
	s_nop 1
	v_or_b32_e32 v214, 32, v140
	v_ashrrev_i32_e32 v215, 31, v214
	v_lshl_add_u64 v[216:217], v[134:135], 0, v[214:215]
	v_mad_u64_u32 v[218:219], s[4:5], v216, s61, v[136:137]
	v_mad_i32_i24 v219, v217, s61, v219
	v_lshl_add_u64 v[218:219], v[218:219], 0, v[220:221]
	v_mul_f32_e32 v118, v118, v182
	v_mul_f32_e32 v119, v119, v183
	v_mul_f32_e32 v120, v120, v184
	v_mul_f32_e32 v121, v121, v185
	v_mul_f32_e32 v86, v86, v190
	v_mul_f32_e32 v87, v87, v191
	v_mul_f32_e32 v88, v88, v192
	v_mul_f32_e32 v89, v89, v193
	v_cvt_pk_bf16_f32 v118, v118, v119
	v_cvt_pk_bf16_f32 v119, v120, v121
	v_cvt_pk_bf16_f32 v120, v86, v87
	v_cvt_pk_bf16_f32 v121, v88, v89
	s_nop 1
	v_permlane16_swap_b32 v118, v120
	v_permlane16_swap_b32 v119, v121
	global_store_dwordx4 v[218:219], v[118:121], off
	v_mul_f32_e32 v54, v54, v198
	v_mul_f32_e32 v55, v55, v199
	v_mul_f32_e32 v56, v56, v200
	v_mul_f32_e32 v57, v57, v201
	v_mul_f32_e32 v22, v22, v206
	v_mul_f32_e32 v23, v23, v207
	v_mul_f32_e32 v24, v24, v208
	v_mul_f32_e32 v25, v25, v209
	v_cvt_pk_bf16_f32 v54, v54, v55
	v_cvt_pk_bf16_f32 v55, v56, v57
	v_cvt_pk_bf16_f32 v56, v22, v23
	v_cvt_pk_bf16_f32 v57, v24, v25
	s_nop 1
	v_permlane16_swap_b32 v54, v56
	v_permlane16_swap_b32 v55, v57
	global_store_dwordx4 v[218:219], v[54:57], off offset:64
	s_nop 1
	v_or_b32_e32 v214, 48, v140
	v_ashrrev_i32_e32 v215, 31, v214
	v_lshl_add_u64 v[216:217], v[134:135], 0, v[214:215]
	v_mad_u64_u32 v[218:219], s[4:5], v216, s61, v[136:137]
	v_mad_i32_i24 v219, v217, s61, v219
	v_lshl_add_u64 v[218:219], v[218:219], 0, v[220:221]
	v_mul_f32_e32 v114, v114, v182
	v_mul_f32_e32 v115, v115, v183
	v_mul_f32_e32 v116, v116, v184
	v_mul_f32_e32 v117, v117, v185
	v_mul_f32_e32 v82, v82, v190
	v_mul_f32_e32 v83, v83, v191
	v_mul_f32_e32 v84, v84, v192
	v_mul_f32_e32 v85, v85, v193
	v_cvt_pk_bf16_f32 v114, v114, v115
	v_cvt_pk_bf16_f32 v115, v116, v117
; __device__ __forceinline__ unsigned pack2(float a, float b) { unsigned r; asm("v_cvt_pk_bf16_f32 %0, %1, %2" : "=v"(r) : "v"(a), "v"(b)); return r; }
;   __device__ __forceinline__ void r4(int g, int rig, int col, f32x4 v) const {
;     const size_t row = (size_t)g * 2304 + rig;
;     const f32x4 t = *(const f32x4*)(part + row) + *(const f32x4*)(part + 18432 + row);
;     f32x4 s;
; #pragma unroll
;     for (int j = 0; j < 4; ++j) s[j] = rsqrtf(t[j] * (1.0f / 256.0f) + 1e-6f);
;     uint2 u; u.x = pack2(v[0] * s[0], v[1] * s[1]); u.y = pack2(v[2] * s[2], v[3] * s[3]);
;     *(uint2*)(out + ((size_t)g * 1024 + col) * 2304 + rig) = u;
;   }
; template <bool SWAP, class Epi, bool THIN = false> ...
;     ...
;     } else if constexpr (Epi::KIND == 1) {
; #pragma unroll
;       for (int m = 0; m < 4; ++m) {
;         const int rig = rig0 + rw + m * 16 + fq_e * 4;
; #pragma unroll
;         for (int n = 0; n < 8; ++n) {
;           const int col = nt * 256 + wc_e * 128 + n * 16 + fr_e;
;           if (col < N) epi.r4(g, rig, col, acc[m][n]);
;         }
;       }
	v_cvt_pk_bf16_f32 v116, v82, v83
	v_cvt_pk_bf16_f32 v117, v84, v85
	s_nop 1
	v_permlane16_swap_b32 v114, v116
	v_permlane16_swap_b32 v115, v117
	global_store_dwordx4 v[218:219], v[114:117], off
	v_mul_f32_e32 v50, v50, v198
	v_mul_f32_e32 v51, v51, v199
	v_mul_f32_e32 v52, v52, v200
	v_mul_f32_e32 v53, v53, v201
	v_mul_f32_e32 v18, v18, v206
	v_mul_f32_e32 v19, v19, v207
	v_mul_f32_e32 v20, v20, v208
	v_mul_f32_e32 v21, v21, v209
	v_cvt_pk_bf16_f32 v50, v50, v51
	v_cvt_pk_bf16_f32 v51, v52, v53
	v_cvt_pk_bf16_f32 v52, v18, v19
	v_cvt_pk_bf16_f32 v53, v20, v21
	s_nop 1
	v_permlane16_swap_b32 v50, v52
	v_permlane16_swap_b32 v51, v53
	global_store_dwordx4 v[218:219], v[50:53], off offset:64
	s_nop 1
	v_or_b32_e32 v214, 64, v140
	v_ashrrev_i32_e32 v215, 31, v214
	v_lshl_add_u64 v[216:217], v[134:135], 0, v[214:215]
	v_mad_u64_u32 v[218:219], s[4:5], v216, s61, v[136:137]
	v_mad_i32_i24 v219, v217, s61, v219
	v_lshl_add_u64 v[218:219], v[218:219], 0, v[220:221]
	v_mul_f32_e32 v110, v110, v182
	v_mul_f32_e32 v111, v111, v183
	v_mul_f32_e32 v112, v112, v184
	v_mul_f32_e32 v113, v113, v185
	v_mul_f32_e32 v78, v78, v190
	v_mul_f32_e32 v79, v79, v191
	v_mul_f32_e32 v80, v80, v192
	v_mul_f32_e32 v81, v81, v193
	v_cvt_pk_bf16_f32 v110, v110, v111
	v_cvt_pk_bf16_f32 v111, v112, v113
	v_cvt_pk_bf16_f32 v112, v78, v79
	v_cvt_pk_bf16_f32 v113, v80, v81
	s_nop 1
	v_permlane16_swap_b32 v110, v112
	v_permlane16_swap_b32 v111, v113
	global_store_dwordx4 v[218:219], v[110:113], off
	v_mul_f32_e32 v46, v46, v198
	v_mul_f32_e32 v47, v47, v199
	v_mul_f32_e32 v48, v48, v200
	v_mul_f32_e32 v49, v49, v201
	v_mul_f32_e32 v14, v14, v206
	v_mul_f32_e32 v15, v15, v207
	v_mul_f32_e32 v16, v16, v208
	v_mul_f32_e32 v17, v17, v209
	v_cvt_pk_bf16_f32 v46, v46, v47
	v_cvt_pk_bf16_f32 v47, v48, v49
	v_cvt_pk_bf16_f32 v48, v14, v15
	v_cvt_pk_bf16_f32 v49, v16, v17
	s_nop 1
	v_permlane16_swap_b32 v46, v48
	v_permlane16_swap_b32 v47, v49
	global_store_dwordx4 v[218:219], v[46:49], off offset:64
	s_nop 1
	v_or_b32_e32 v214, 80, v140
	v_ashrrev_i32_e32 v215, 31, v214
	v_lshl_add_u64 v[216:217], v[134:135], 0, v[214:215]
	v_mad_u64_u32 v[218:219], s[4:5], v216, s61, v[136:137]
	v_mad_i32_i24 v219, v217, s61, v219
	v_lshl_add_u64 v[218:219], v[218:219], 0, v[220:221]
	v_mul_f32_e32 v106, v106, v182
	v_mul_f32_e32 v107, v107, v183
	v_mul_f32_e32 v108, v108, v184
	v_mul_f32_e32 v109, v109, v185
	v_mul_f32_e32 v74, v74, v190
	v_mul_f32_e32 v75, v75, v191
	v_mul_f32_e32 v76, v76, v192
	v_mul_f32_e32 v77, v77, v193
	v_cvt_pk_bf16_f32 v106, v106, v107
	v_cvt_pk_bf16_f32 v107, v108, v109
	v_cvt_pk_bf16_f32 v108, v74, v75
	v_cvt_pk_bf16_f32 v109, v76, v77
	s_nop 1
	v_permlane16_swap_b32 v106, v108
	v_permlane16_swap_b32 v107, v109
	global_store_dwordx4 v[218:219], v[106:109], off
	v_mul_f32_e32 v42, v42, v198
	v_mul_f32_e32 v43, v43, v199
	v_mul_f32_e32 v44, v44, v200
	v_mul_f32_e32 v45, v45, v201
	v_mul_f32_e32 v10, v10, v206
	v_mul_f32_e32 v11, v11, v207
	v_mul_f32_e32 v12, v12, v208
	v_mul_f32_e32 v13, v13, v209
	v_cvt_pk_bf16_f32 v42, v42, v43
	v_cvt_pk_bf16_f32 v43, v44, v45
	v_cvt_pk_bf16_f32 v44, v10, v11
	v_cvt_pk_bf16_f32 v45, v12, v13
	s_nop 1
	v_permlane16_swap_b32 v42, v44
	v_permlane16_swap_b32 v43, v45
	global_store_dwordx4 v[218:219], v[42:45], off offset:64
	s_nop 1
	v_or_b32_e32 v214, 96, v140
	v_ashrrev_i32_e32 v215, 31, v214
	v_lshl_add_u64 v[216:217], v[134:135], 0, v[214:215]
	v_mad_u64_u32 v[218:219], s[4:5], v216, s61, v[136:137]
	v_mad_i32_i24 v219, v217, s61, v219
	v_lshl_add_u64 v[218:219], v[218:219], 0, v[220:221]
	v_mul_f32_e32 v102, v102, v182
	v_mul_f32_e32 v103, v103, v183
	v_mul_f32_e32 v104, v104, v184
	v_mul_f32_e32 v105, v105, v185
	v_mul_f32_e32 v70, v70, v190
	v_mul_f32_e32 v71, v71, v191
	v_mul_f32_e32 v72, v72, v192
	v_mul_f32_e32 v73, v73, v193
	v_cvt_pk_bf16_f32 v102, v102, v103
	v_cvt_pk_bf16_f32 v103, v104, v105
	v_cvt_pk_bf16_f32 v104, v70, v71
	v_cvt_pk_bf16_f32 v105, v72, v73
	s_nop 1
	v_permlane16_swap_b32 v102, v104
	v_permlane16_swap_b32 v103, v105
	global_store_dwordx4 v[218:219], v[102:105], off
	v_mul_f32_e32 v38, v38, v198
	v_mul_f32_e32 v39, v39, v199
	v_mul_f32_e32 v40, v40, v200
	v_mul_f32_e32 v41, v41, v201
	v_mul_f32_e32 v6, v6, v206
	v_mul_f32_e32 v7, v7, v207
	v_mul_f32_e32 v8, v8, v208
	v_mul_f32_e32 v9, v9, v209
	v_cvt_pk_bf16_f32 v38, v38, v39
	v_cvt_pk_bf16_f32 v39, v40, v41
	v_cvt_pk_bf16_f32 v40, v6, v7
	v_cvt_pk_bf16_f32 v41, v8, v9
	s_nop 1
	v_permlane16_swap_b32 v38, v40
	v_permlane16_swap_b32 v39, v41
	global_store_dwordx4 v[218:219], v[38:41], off offset:64
	s_nop 1
	v_or_b32_e32 v214, 112, v140
	v_ashrrev_i32_e32 v215, 31, v214
	v_lshl_add_u64 v[216:217], v[134:135], 0, v[214:215]
	v_mad_u64_u32 v[218:219], s[4:5], v216, s61, v[136:137]
	v_mad_i32_i24 v219, v217, s61, v219
	v_lshl_add_u64 v[218:219], v[218:219], 0, v[220:221]
	v_mul_f32_e32 v98, v98, v182
	v_mul_f32_e32 v99, v99, v183
	v_mul_f32_e32 v100, v100, v184
	v_mul_f32_e32 v101, v101, v185
	v_mul_f32_e32 v66, v66, v190
	v_mul_f32_e32 v67, v67, v191
	v_mul_f32_e32 v68, v68, v192
	v_mul_f32_e32 v69, v69, v193
	v_cvt_pk_bf16_f32 v98, v98, v99
	v_cvt_pk_bf16_f32 v99, v100, v101
	v_cvt_pk_bf16_f32 v100, v66, v67
	v_cvt_pk_bf16_f32 v101, v68, v69
	s_nop 1
	v_permlane16_swap_b32 v98, v100
	v_permlane16_swap_b32 v99, v101
	global_store_dwordx4 v[218:219], v[98:101], off
	v_mul_f32_e32 v34, v34, v198
	v_mul_f32_e32 v35, v35, v199
	v_mul_f32_e32 v36, v36, v200
	v_mul_f32_e32 v37, v37, v201
	v_mul_f32_e32 v2, v2, v206
	v_mul_f32_e32 v3, v3, v207
	v_mul_f32_e32 v4, v4, v208
	v_mul_f32_e32 v5, v5, v209
	v_cvt_pk_bf16_f32 v34, v34, v35
	v_cvt_pk_bf16_f32 v35, v36, v37
	v_cvt_pk_bf16_f32 v36, v2, v3
	v_cvt_pk_bf16_f32 v37, v4, v5
	s_nop 1
	v_permlane16_swap_b32 v34, v36
	v_permlane16_swap_b32 v35, v37
	global_store_dwordx4 v[218:219], v[34:37], off offset:64
	s_nop 1
	s_branch .LBB0_1886
